# select search: negative-threshold case interpolates the count below the probe on the |v|^1.5 scale; value bisection once 4 or fewer elements remain in the bracket
# speedup vs baseline: 1.0036x; 1.0036x over previous
; __device__ __forceinline__ int wave_isum(int v) {
;     v += __builtin_amdgcn_update_dpp(0, v, 0x111, 0xf, 0xf, false);
;     v += __builtin_amdgcn_update_dpp(0, v, 0x112, 0xf, 0xf, false);
;     v += __builtin_amdgcn_update_dpp(0, v, 0x114, 0xf, 0xf, false);
;     v += __builtin_amdgcn_update_dpp(0, v, 0x118, 0xf, 0xf, false);
;     v += __builtin_amdgcn_update_dpp(0, v, 0x142, 0xa, 0xf, false);
;     v += __builtin_amdgcn_update_dpp(0, v, 0x143, 0xc, 0xf, false);
;     return __builtin_amdgcn_readlane(v, 63);
; }
; __device__ __forceinline__ void select_query(const unsigned (&u)[64], unsigned vmax, int q, int b, int lane, unsigned* MASKb) {
;     ...
;         const int cpos = count_ge(u, K0 + 1u, nblk);
;         if (cpos == 256) { T = K0 + 1u; exact = true; done = true; }
;         else if (cpos > 256) { lo = K0 + 1u; Llo = __log2f((float)cpos) - L256; hi = kmax + 1u; Lhi = L256 + 1.f; }
.Lsqa_red:
	v_add_u32_e32 v0, v0, v34
	s_nop 1
	v_add_u32_dpp v0, v0, v0 row_shr:1 row_mask:0xf bank_mask:0xf bound_ctrl:1
	s_nop 1
	v_add_u32_dpp v0, v0, v0 row_shr:2 row_mask:0xf bank_mask:0xf bound_ctrl:1
	s_nop 1
	v_add_u32_dpp v0, v0, v0 row_shr:4 row_mask:0xf bank_mask:0xf bound_ctrl:1
	s_nop 1
	v_add_u32_dpp v0, v0, v0 row_shr:8 row_mask:0xf bank_mask:0xf bound_ctrl:1
	s_nop 1
	v_add_u32_dpp v0, v0, v0 row_bcast:15 row_mask:0xa bank_mask:0xf
	s_nop 1
	v_add_u32_dpp v0, v0, v0 row_bcast:31 row_mask:0xc bank_mask:0xf
	s_nop 0
	v_readlane_b32 s24, v0, 63
	s_cmp_eq_u32 s21, 2
	s_cbranch_scc1 .Lsqa_st2
	s_cmp_eq_u32 s21, 1
	s_cbranch_scc1 .Lsqa_st1
	s_cmpk_eq_i32 s24, 0x100
	s_cbranch_scc1 .Lsqa_exact
	s_cmpk_gt_i32 s24, 0x100
	s_cbranch_scc0 .Lsqa_s0lt
	s_mov_b32 s13, 0x80000001
	s_add_i32 s12, s19, 1
	s_mov_b32 s15, 0
	v_cvt_f32_u32_e32 v35, s24
	v_log_f32_e32 v35, v35
	v_mov_b32_e32 v36, 0x41200b88
	v_add_f32_e32 v35, 0xc1000b88, v35
	s_and_b32 s26, s12, 0x7fffffff
	s_bfe_u32 s27, s26, 0x80017
	s_sub_u32 s27, s27, 0x43
	s_cmp_lt_u32 s27, 0x79
	s_cselect_b32 s101, 1, 0
	v_sqrt_f32_e32 v193, s26
	v_mov_b32_e32 v192, 0
	v_mul_f32_e32 v193, s26, v193
	s_mov_b32 s98, s24
	s_mov_b32 s99, 0
	s_mov_b32 s22, 0
	s_mov_b32 s23, 0
	s_mov_b32 s21, 2
	s_branch .Lsqa_next

; __device__ __forceinline__ void select_query(const unsigned (&u)[64], unsigned vmax, int q, int b, int lane, unsigned* MASKb) {
;     ...
;                 unsigned vmin = 0xffffffffu;
; #pragma unroll
;                 for (int i = 0; i < 64; ++i) vmin = min(vmin, u[i] - 1u);
;                 lo = ~wave_umax(~vmin) + 1u; Llo = __log2f((float)n) - L256; hi = K0; Lhi = L256 - __log2f(fmaxf((float)c0, 0.5f));
;     ...
;             const int c = count_ge(u, mid, nblk);
;             if (c == 256) { T = mid; exact = true; break; }
;             if (c > 256) { lo = mid; Llo = __log2f((float)c) - L256; if (last == 1) Lhi *= 0.5f; last = 1; }
.Lsqa_s1lt:
	v_mov_b32_e32 v191, -1
	v_add_u32_e32 v0, -1, v138
	v_min_u32_e32 v191, v191, v0
	v_add_u32_e32 v0, -1, v140
	v_min_u32_e32 v191, v191, v0
	v_add_u32_e32 v0, -1, v139
	v_min_u32_e32 v191, v191, v0
	v_add_u32_e32 v0, -1, v141
	v_min_u32_e32 v191, v191, v0
	v_add_u32_e32 v0, -1, v142
	v_min_u32_e32 v191, v191, v0
	v_add_u32_e32 v0, -1, v146
	v_min_u32_e32 v191, v191, v0
	v_add_u32_e32 v0, -1, v143
	v_min_u32_e32 v191, v191, v0
	v_add_u32_e32 v0, -1, v147
	v_min_u32_e32 v191, v191, v0
	v_add_u32_e32 v0, -1, v144
	v_min_u32_e32 v191, v191, v0
	v_add_u32_e32 v0, -1, v148
	v_min_u32_e32 v191, v191, v0
	v_add_u32_e32 v0, -1, v145
	v_min_u32_e32 v191, v191, v0
	v_add_u32_e32 v0, -1, v149
	v_min_u32_e32 v191, v191, v0
	v_add_u32_e32 v0, -1, v150
	v_min_u32_e32 v191, v191, v0
	v_add_u32_e32 v0, -1, v152
	v_min_u32_e32 v191, v191, v0
	v_add_u32_e32 v0, -1, v151
	v_min_u32_e32 v191, v191, v0
	v_add_u32_e32 v0, -1, v154
	v_min_u32_e32 v191, v191, v0
	v_add_u32_e32 v0, -1, v153
	v_min_u32_e32 v191, v191, v0
	v_add_u32_e32 v0, -1, v156
	v_min_u32_e32 v191, v191, v0
	v_add_u32_e32 v0, -1, v155
	v_min_u32_e32 v191, v191, v0
	v_add_u32_e32 v0, -1, v157
	v_min_u32_e32 v191, v191, v0
	v_add_u32_e32 v0, -1, v158
	v_min_u32_e32 v191, v191, v0
	v_add_u32_e32 v0, -1, v160
	v_min_u32_e32 v191, v191, v0
	v_add_u32_e32 v0, -1, v159
	v_min_u32_e32 v191, v191, v0
	v_add_u32_e32 v0, -1, v161
	v_min_u32_e32 v191, v191, v0
	v_add_u32_e32 v0, -1, v167
	v_min_u32_e32 v191, v191, v0
	v_add_u32_e32 v0, -1, v169
	v_min_u32_e32 v191, v191, v0
	v_add_u32_e32 v0, -1, v168
	v_min_u32_e32 v191, v191, v0
	v_add_u32_e32 v0, -1, v170
	v_min_u32_e32 v191, v191, v0
	v_add_u32_e32 v0, -1, v173
	v_min_u32_e32 v191, v191, v0
	v_add_u32_e32 v0, -1, v174
	v_min_u32_e32 v191, v191, v0
	v_add_u32_e32 v0, -1, v175
	v_min_u32_e32 v191, v191, v0
	v_add_u32_e32 v0, -1, v176
	v_min_u32_e32 v191, v191, v0
	v_add_u32_e32 v0, -1, v76
	v_min_u32_e32 v191, v191, v0
	v_add_u32_e32 v0, -1, v78
	v_min_u32_e32 v191, v191, v0
	v_add_u32_e32 v0, -1, v77
	v_min_u32_e32 v191, v191, v0
	v_add_u32_e32 v0, -1, v79
	v_min_u32_e32 v191, v191, v0
	v_add_u32_e32 v0, -1, v80
	v_min_u32_e32 v191, v191, v0
	v_add_u32_e32 v0, -1, v84
	v_min_u32_e32 v191, v191, v0
	v_add_u32_e32 v0, -1, v81
	v_min_u32_e32 v191, v191, v0
	v_add_u32_e32 v0, -1, v85
	v_min_u32_e32 v191, v191, v0
	v_add_u32_e32 v0, -1, v82
	v_min_u32_e32 v191, v191, v0
	v_add_u32_e32 v0, -1, v86
	v_min_u32_e32 v191, v191, v0
	v_add_u32_e32 v0, -1, v83
	v_min_u32_e32 v191, v191, v0
	v_add_u32_e32 v0, -1, v87
	v_min_u32_e32 v191, v191, v0
	v_add_u32_e32 v0, -1, v89
	v_min_u32_e32 v191, v191, v0
	v_add_u32_e32 v0, -1, v91
	v_min_u32_e32 v191, v191, v0
	v_add_u32_e32 v0, -1, v90
	v_min_u32_e32 v191, v191, v0
	v_add_u32_e32 v0, -1, v93
	v_min_u32_e32 v191, v191, v0
	v_add_u32_e32 v0, -1, v92
	v_min_u32_e32 v191, v191, v0
	v_add_u32_e32 v0, -1, v95
	v_min_u32_e32 v191, v191, v0
	v_add_u32_e32 v0, -1, v94
	v_min_u32_e32 v191, v191, v0
	v_add_u32_e32 v0, -1, v96
	v_min_u32_e32 v191, v191, v0
	v_add_u32_e32 v0, -1, v97
	v_min_u32_e32 v191, v191, v0
	v_add_u32_e32 v0, -1, v172
	v_min_u32_e32 v191, v191, v0
	v_add_u32_e32 v0, -1, v171
	v_min_u32_e32 v191, v191, v0
	v_add_u32_e32 v0, -1, v178
	v_min_u32_e32 v191, v191, v0
	v_add_u32_e32 v0, -1, v180
	v_min_u32_e32 v191, v191, v0
	v_add_u32_e32 v0, -1, v183
	v_min_u32_e32 v191, v191, v0
	v_add_u32_e32 v0, -1, v182
	v_min_u32_e32 v191, v191, v0
	v_add_u32_e32 v0, -1, v184
	v_min_u32_e32 v191, v191, v0
	v_add_u32_e32 v0, -1, v186
	v_min_u32_e32 v191, v191, v0
	v_add_u32_e32 v0, -1, v187
	v_min_u32_e32 v191, v191, v0
	v_add_u32_e32 v0, -1, v188
	v_min_u32_e32 v191, v191, v0
	v_add_u32_e32 v0, -1, v189
	v_min_u32_e32 v191, v191, v0
	v_not_b32_e32 v191, v191
	s_nop 1
	v_max_u32_dpp v191, v191, v191 row_shr:1 row_mask:0xf bank_mask:0xf bound_ctrl:1
	s_nop 1
	v_max_u32_dpp v191, v191, v191 row_shr:2 row_mask:0xf bank_mask:0xf bound_ctrl:1
	s_nop 1
	v_max_u32_dpp v191, v191, v191 row_shr:4 row_mask:0xf bank_mask:0xf bound_ctrl:1
	s_nop 1
	v_max_u32_dpp v191, v191, v191 row_shr:8 row_mask:0xf bank_mask:0xf bound_ctrl:1
	s_nop 1
	v_max_u32_dpp v191, v191, v191 row_bcast:15 row_mask:0xa bank_mask:0xf
	s_nop 1
	v_max_u32_dpp v191, v191, v191 row_bcast:31 row_mask:0xc bank_mask:0xf
	s_nop 0
	v_readlane_b32 s26, v191, 63
	s_sub_i32 s13, 0, s26
	s_mov_b32 s12, 0x80000000
	s_mov_b32 s15, s24
	s_add_i32 s26, s75, 1
	s_mov_b32 s98, s26
	s_mov_b32 s99, 1
	s_sub_i32 s27, s26, 0x100
	v_cvt_f32_u32_e32 v202, s27
	s_sub_i32 s27, s26, s24
	v_cvt_f32_u32_e32 v36, s27
	v_add_f32_e32 v202, 0.5, v202
	v_add_f32_e32 v36, 0.5, v36
	v_log_f32_e32 v202, v202
	v_log_f32_e32 v36, v36
	s_not_b32 s27, s13
	s_and_b32 s27, s27, 0x7fffffff
	s_bfe_u32 s28, s27, 0x80017
	s_sub_u32 s28, s28, 0x43
	s_cmp_lt_u32 s28, 0x79
	s_cselect_b32 s101, 1, 0
	v_add_f32_e32 v35, 1.0, v202
	v_sub_f32_e32 v36, v36, v202
	v_sqrt_f32_e32 v192, s27
	v_mov_b32_e32 v193, 0
	v_mul_f32_e32 v192, s27, v192
	s_mov_b32 s22, 0
	s_mov_b32 s23, 0
	s_mov_b32 s21, 2
	s_branch .Lsqa_next
.Lsqa_st2:
	s_cmpk_eq_i32 s24, 0x100
	s_cbranch_scc1 .Lsqa_exact
	s_cmpk_gt_i32 s24, 0x100
	s_cbranch_scc0 .Lsqa_s2lt
	s_mov_b32 s13, s14
	s_mov_b32 s98, s24
	v_mov_b32_e32 v192, v88
	s_cmp_eq_u32 s99, 0
	s_cbranch_scc1 .Lsqa_s2ap
	s_add_i32 s27, s75, 1
	s_sub_i32 s27, s27, s24
	v_cvt_f32_u32_e32 v35, s27
	v_add_f32_e32 v35, 0.5, v35
	v_log_f32_e32 v35, v35
	s_cmp_lg_u32 s23, 1
	s_cbranch_scc1 .Lsqa_s2an
	v_mul_f32_e32 v36, 0x3f400000, v36
.Lsqa_s2an:
	v_sub_f32_e32 v35, v202, v35
	s_branch .Lsqa_s2aj
.Lsqa_s2ap:
	v_cvt_f32_u32_e32 v35, s24
	v_log_f32_e32 v35, v35
	s_cmp_lg_u32 s23, 1
	s_cbranch_scc1 .Lsqa_s2a
	v_mul_f32_e32 v36, 0x3f400000, v36

; __device__ __forceinline__ void select_query(const unsigned (&u)[64], unsigned vmax, int q, int b, int lane, unsigned* MASKb) {
;     ...
;             if (c > 256) { lo = mid; Llo = __log2f((float)c) - L256; if (last == 1) Lhi *= 0.5f; last = 1; }
;             else { hi = mid; Lhi = L256 - __log2f(fmaxf((float)c, 0.5f)); if (last == 2) Llo *= 0.5f; last = 2; }
.Lsqa_s2aj:
	s_mov_b32 s23, 1
	s_add_i32 s22, s22, 1
	s_branch .Lsqa_next
.Lsqa_s2lt:
	s_mov_b32 s12, s14
	s_mov_b32 s15, s24
	v_mov_b32_e32 v193, v88
	s_cmp_eq_u32 s99, 0
	s_cbranch_scc1 .Lsqa_s2bp
	s_add_i32 s27, s75, 1
	s_sub_i32 s27, s27, s24
	v_cvt_f32_u32_e32 v36, s27
	v_add_f32_e32 v36, 0.5, v36
	v_log_f32_e32 v36, v36
	s_cmp_lg_u32 s23, 2
	s_cbranch_scc1 .Lsqa_s2bn
	v_mul_f32_e32 v35, 0x3f400000, v35
.Lsqa_s2bn:
	v_sub_f32_e32 v36, v36, v202
	s_branch .Lsqa_s2bj
.Lsqa_s2bp:
	v_cvt_f32_u32_e32 v36, s24
	v_max_f32_e32 v36, 0.5, v36
	v_log_f32_e32 v36, v36
	s_cmp_lg_u32 s23, 2
	s_cbranch_scc1 .Lsqa_s2b
	v_mul_f32_e32 v35, 0x3f400000, v35

; __device__ __forceinline__ float keyval(unsigned k) { return __uint_as_float((k & 0x80000000u) ? (k ^ 0x80000000u) : ~k); }
; __device__ __forceinline__ unsigned valkey(float f) { const unsigned b = __float_as_uint(f); return b ^ ((unsigned)((int)b >> 31) | 0x80000000u); }
; __device__ __forceinline__ void select_query(const unsigned (&u)[64], unsigned vmax, int q, int b, int lane, unsigned* MASKb) {
;     ...
;         while (!done) {
;             if (hi - lo <= 1u) { T = lo; exact = false; break; }
;             const float vlo = keyval(lo), vhi = keyval(hi);
;             const float frac = (it >= 9 && (it & 1)) ? 0.5f : Llo * __builtin_amdgcn_rcpf(Llo + Lhi);
;             unsigned mid = valkey(vlo + frac * (vhi - vlo));
;             if (mid <= lo) mid = lo + 1u;
;             if (mid >= hi) mid = hi - 1u;
.Lsqa_s2bj:
	s_mov_b32 s23, 2
	s_add_i32 s22, s22, 1
.Lsqa_next:
	s_sub_u32 s26, s12, s13
	s_cmp_lt_u32 s26, 2
	s_cbranch_scc1 .Lsqa_collapse
	s_sub_u32 s26, s98, s15
	s_cmp_le_u32 s26, 4
	s_cbranch_scc1 .Lsqa_endg
	s_cmp_eq_u32 s101, 0
	s_cbranch_scc1 .Lsqa_lin
	s_cmp_lt_i32 s22, 9
	s_cbranch_scc0 .Lsqa_lin
	v_add_f32_e32 v191, v35, v36
	v_sub_f32_e32 v34, v193, v192
	v_rcp_f32_e32 v191, v191
	s_nop 0
	v_mul_f32_e32 v191, v35, v191
	v_fma_f32 v88, v191, v34, v192
	v_log_f32_e32 v0, v88
	s_nop 0
	v_mul_f32_e32 v0, 0x3f2aaaab, v0
	v_exp_f32_e32 v191, v0
	s_nop 0
	s_cmp_eq_u32 s99, 0
	s_cbranch_scc1 .Lsqa_key
	v_xor_b32_e32 v191, 0x80000000, v191
	s_branch .Lsqa_key

; __device__ __forceinline__ float keyval(unsigned k) { return __uint_as_float((k & 0x80000000u) ? (k ^ 0x80000000u) : ~k); }
; __device__ __forceinline__ unsigned valkey(float f) { const unsigned b = __float_as_uint(f); return b ^ ((unsigned)((int)b >> 31) | 0x80000000u); }
; __device__ __forceinline__ void select_query(const unsigned (&u)[64], unsigned vmax, int q, int b, int lane, unsigned* MASKb) {
;     ...
;             if (hi - lo <= 1u) { T = lo; exact = false; break; }
;             const float vlo = keyval(lo), vhi = keyval(hi);
;             const float frac = (it >= 9 && (it & 1)) ? 0.5f : Llo * __builtin_amdgcn_rcpf(Llo + Lhi);
;             unsigned mid = valkey(vlo + frac * (vhi - vlo));
.Lsqa_endg:
	s_cmp_gt_i32 s13, -1
	s_cselect_b32 s26, -1, 0x80000000
	s_xor_b32 s16, s13, s26
	s_cmp_gt_i32 s12, -1
	s_cselect_b32 s26, -1, 0x80000000
	s_xor_b32 s17, s12, s26
	v_mov_b32_e32 v191, 0.5
	s_branch .Lsqa_frac

; __device__ __forceinline__ int wave_isum(int v) {
;     v += __builtin_amdgcn_update_dpp(0, v, 0x111, 0xf, 0xf, false);
;     v += __builtin_amdgcn_update_dpp(0, v, 0x112, 0xf, 0xf, false);
;     v += __builtin_amdgcn_update_dpp(0, v, 0x114, 0xf, 0xf, false);
;     v += __builtin_amdgcn_update_dpp(0, v, 0x118, 0xf, 0xf, false);
;     v += __builtin_amdgcn_update_dpp(0, v, 0x142, 0xa, 0xf, false);
;     v += __builtin_amdgcn_update_dpp(0, v, 0x143, 0xc, 0xf, false);
;     return __builtin_amdgcn_readlane(v, 63);
; }
; __device__ __forceinline__ void select_query(const unsigned (&u)[64], unsigned vmax, int q, int b, int lane, unsigned* MASKb) {
;     ...
;         const int cpos = count_ge(u, K0 + 1u, nblk);
;         if (cpos == 256) { T = K0 + 1u; exact = true; done = true; }
;         else if (cpos > 256) { lo = K0 + 1u; Llo = __log2f((float)cpos) - L256; hi = kmax + 1u; Lhi = L256 + 1.f; }
.Lsqb_red:
	v_add_u32_e32 v138, v138, v140
	s_nop 1
	v_add_u32_dpp v138, v138, v138 row_shr:1 row_mask:0xf bank_mask:0xf bound_ctrl:1
	s_nop 1
	v_add_u32_dpp v138, v138, v138 row_shr:2 row_mask:0xf bank_mask:0xf bound_ctrl:1
	s_nop 1
	v_add_u32_dpp v138, v138, v138 row_shr:4 row_mask:0xf bank_mask:0xf bound_ctrl:1
	s_nop 1
	v_add_u32_dpp v138, v138, v138 row_shr:8 row_mask:0xf bank_mask:0xf bound_ctrl:1
	s_nop 1
	v_add_u32_dpp v138, v138, v138 row_bcast:15 row_mask:0xa bank_mask:0xf
	s_nop 1
	v_add_u32_dpp v138, v138, v138 row_bcast:31 row_mask:0xc bank_mask:0xf
	s_nop 0
	v_readlane_b32 s24, v138, 63
	s_cmp_eq_u32 s21, 2
	s_cbranch_scc1 .Lsqb_st2
	s_cmp_eq_u32 s21, 1
	s_cbranch_scc1 .Lsqb_st1
	s_cmpk_eq_i32 s24, 0x100
	s_cbranch_scc1 .Lsqb_exact
	s_cmpk_gt_i32 s24, 0x100
	s_cbranch_scc0 .Lsqb_s0lt
	s_mov_b32 s13, 0x80000001
	s_add_i32 s12, s19, 1
	s_mov_b32 s15, 0
	v_cvt_f32_u32_e32 v139, s24
	v_log_f32_e32 v139, v139
	v_mov_b32_e32 v141, 0x41200b88
	v_add_f32_e32 v139, 0xc1000b88, v139
	s_and_b32 s26, s12, 0x7fffffff
	s_bfe_u32 s27, s26, 0x80017
	s_sub_u32 s27, s27, 0x43
	s_cmp_lt_u32 s27, 0x79
	s_cselect_b32 s101, 1, 0
	v_sqrt_f32_e32 v77, s26
	v_mov_b32_e32 v76, 0
	v_mul_f32_e32 v77, s26, v77
	s_mov_b32 s98, s24
	s_mov_b32 s99, 0
	s_mov_b32 s22, 0
	s_mov_b32 s23, 0
	s_mov_b32 s21, 2
	s_branch .Lsqb_next

; __device__ __forceinline__ void select_query(const unsigned (&u)[64], unsigned vmax, int q, int b, int lane, unsigned* MASKb) {
;     ...
;                 unsigned vmin = 0xffffffffu;
; #pragma unroll
;                 for (int i = 0; i < 64; ++i) vmin = min(vmin, u[i] - 1u);
;                 lo = ~wave_umax(~vmin) + 1u; Llo = __log2f((float)n) - L256; hi = K0; Lhi = L256 - __log2f(fmaxf((float)c0, 0.5f));
;     ...
;             const int c = count_ge(u, mid, nblk);
;             if (c == 256) { T = mid; exact = true; break; }
;             if (c > 256) { lo = mid; Llo = __log2f((float)c) - L256; if (last == 1) Lhi *= 0.5f; last = 1; }
.Lsqb_s1lt:
	v_mov_b32_e32 v142, -1
	v_add_u32_e32 v138, -1, v98
	v_min_u32_e32 v142, v142, v138
	v_add_u32_e32 v138, -1, v107
	v_min_u32_e32 v142, v142, v138
	v_add_u32_e32 v138, -1, v99
	v_min_u32_e32 v142, v142, v138
	v_add_u32_e32 v138, -1, v108
	v_min_u32_e32 v142, v142, v138
	v_add_u32_e32 v138, -1, v109
	v_min_u32_e32 v142, v142, v138
	v_add_u32_e32 v138, -1, v113
	v_min_u32_e32 v142, v142, v138
	v_add_u32_e32 v138, -1, v110
	v_min_u32_e32 v142, v142, v138
	v_add_u32_e32 v138, -1, v114
	v_min_u32_e32 v142, v142, v138
	v_add_u32_e32 v138, -1, v111
	v_min_u32_e32 v142, v142, v138
	v_add_u32_e32 v138, -1, v115
	v_min_u32_e32 v142, v142, v138
	v_add_u32_e32 v138, -1, v112
	v_min_u32_e32 v142, v142, v138
	v_add_u32_e32 v138, -1, v116
	v_min_u32_e32 v142, v142, v138
	v_add_u32_e32 v138, -1, v117
	v_min_u32_e32 v142, v142, v138
	v_add_u32_e32 v138, -1, v119
	v_min_u32_e32 v142, v142, v138
	v_add_u32_e32 v138, -1, v118
	v_min_u32_e32 v142, v142, v138
	v_add_u32_e32 v138, -1, v121
	v_min_u32_e32 v142, v142, v138
	v_add_u32_e32 v138, -1, v120
	v_min_u32_e32 v142, v142, v138
	v_add_u32_e32 v138, -1, v123
	v_min_u32_e32 v142, v142, v138
	v_add_u32_e32 v138, -1, v122
	v_min_u32_e32 v142, v142, v138
	v_add_u32_e32 v138, -1, v124
	v_min_u32_e32 v142, v142, v138
	v_add_u32_e32 v138, -1, v125
	v_min_u32_e32 v142, v142, v138
	v_add_u32_e32 v138, -1, v127
	v_min_u32_e32 v142, v142, v138
	v_add_u32_e32 v138, -1, v126
	v_min_u32_e32 v142, v142, v138
	v_add_u32_e32 v138, -1, v128
	v_min_u32_e32 v142, v142, v138
	v_add_u32_e32 v138, -1, v129
	v_min_u32_e32 v142, v142, v138
	v_add_u32_e32 v138, -1, v131
	v_min_u32_e32 v142, v142, v138
	v_add_u32_e32 v138, -1, v130
	v_min_u32_e32 v142, v142, v138
	v_add_u32_e32 v138, -1, v132
	v_min_u32_e32 v142, v142, v138
	v_add_u32_e32 v138, -1, v133
	v_min_u32_e32 v142, v142, v138
	v_add_u32_e32 v138, -1, v134
	v_min_u32_e32 v142, v142, v138
	v_add_u32_e32 v138, -1, v136
	v_min_u32_e32 v142, v142, v138
	v_add_u32_e32 v138, -1, v137
	v_min_u32_e32 v142, v142, v138
	v_add_u32_e32 v138, -1, v46
	v_min_u32_e32 v142, v142, v138
	v_add_u32_e32 v138, -1, v48
	v_min_u32_e32 v142, v142, v138
	v_add_u32_e32 v138, -1, v47
	v_min_u32_e32 v142, v142, v138
	v_add_u32_e32 v138, -1, v49
	v_min_u32_e32 v142, v142, v138
	v_add_u32_e32 v138, -1, v42
	v_min_u32_e32 v142, v142, v138
	v_add_u32_e32 v138, -1, v50
	v_min_u32_e32 v142, v142, v138
	v_add_u32_e32 v138, -1, v43
	v_min_u32_e32 v142, v142, v138
	v_add_u32_e32 v138, -1, v44
	v_min_u32_e32 v142, v142, v138
	v_add_u32_e32 v138, -1, v38
	v_min_u32_e32 v142, v142, v138
	v_add_u32_e32 v138, -1, v45
	v_min_u32_e32 v142, v142, v138
	v_add_u32_e32 v138, -1, v39
	v_min_u32_e32 v142, v142, v138
	v_add_u32_e32 v138, -1, v40
	v_min_u32_e32 v142, v142, v138
	v_add_u32_e32 v138, -1, v41
	v_min_u32_e32 v142, v142, v138
	v_add_u32_e32 v138, -1, v52
	v_min_u32_e32 v142, v142, v138
	v_add_u32_e32 v138, -1, v51
	v_min_u32_e32 v142, v142, v138
	v_add_u32_e32 v138, -1, v54
	v_min_u32_e32 v142, v142, v138
	v_add_u32_e32 v138, -1, v53
	v_min_u32_e32 v142, v142, v138
	v_add_u32_e32 v138, -1, v56
	v_min_u32_e32 v142, v142, v138
	v_add_u32_e32 v138, -1, v55
	v_min_u32_e32 v142, v142, v138
	v_add_u32_e32 v138, -1, v57
	v_min_u32_e32 v142, v142, v138
	v_add_u32_e32 v138, -1, v58
	v_min_u32_e32 v142, v142, v138
	v_add_u32_e32 v138, -1, v60
	v_min_u32_e32 v142, v142, v138
	v_add_u32_e32 v138, -1, v59
	v_min_u32_e32 v142, v142, v138
	v_add_u32_e32 v138, -1, v61
	v_min_u32_e32 v142, v142, v138
	v_add_u32_e32 v138, -1, v62
	v_min_u32_e32 v142, v142, v138
	v_add_u32_e32 v138, -1, v64
	v_min_u32_e32 v142, v142, v138
	v_add_u32_e32 v138, -1, v63
	v_min_u32_e32 v142, v142, v138
	v_add_u32_e32 v138, -1, v65
	v_min_u32_e32 v142, v142, v138
	v_add_u32_e32 v138, -1, v72
	v_min_u32_e32 v142, v142, v138
	v_add_u32_e32 v138, -1, v73
	v_min_u32_e32 v142, v142, v138
	v_add_u32_e32 v138, -1, v74
	v_min_u32_e32 v142, v142, v138
	v_add_u32_e32 v138, -1, v75
	v_min_u32_e32 v142, v142, v138
	v_not_b32_e32 v142, v142
	s_nop 1
	v_max_u32_dpp v142, v142, v142 row_shr:1 row_mask:0xf bank_mask:0xf bound_ctrl:1
	s_nop 1
	v_max_u32_dpp v142, v142, v142 row_shr:2 row_mask:0xf bank_mask:0xf bound_ctrl:1
	s_nop 1
	v_max_u32_dpp v142, v142, v142 row_shr:4 row_mask:0xf bank_mask:0xf bound_ctrl:1
	s_nop 1
	v_max_u32_dpp v142, v142, v142 row_shr:8 row_mask:0xf bank_mask:0xf bound_ctrl:1
	s_nop 1
	v_max_u32_dpp v142, v142, v142 row_bcast:15 row_mask:0xa bank_mask:0xf
	s_nop 1
	v_max_u32_dpp v142, v142, v142 row_bcast:31 row_mask:0xc bank_mask:0xf
	s_nop 0
	v_readlane_b32 s26, v142, 63
	s_sub_i32 s13, 0, s26
	s_mov_b32 s12, 0x80000000
	s_mov_b32 s15, s24
	s_add_i32 s26, s75, 2
	s_mov_b32 s98, s26
	s_mov_b32 s99, 1
	s_sub_i32 s27, s26, 0x100
	v_cvt_f32_u32_e32 v202, s27
	s_sub_i32 s27, s26, s24
	v_cvt_f32_u32_e32 v141, s27
	v_add_f32_e32 v202, 0.5, v202
	v_add_f32_e32 v141, 0.5, v141
	v_log_f32_e32 v202, v202
	v_log_f32_e32 v141, v141
	s_not_b32 s27, s13
	s_and_b32 s27, s27, 0x7fffffff
	s_bfe_u32 s28, s27, 0x80017
	s_sub_u32 s28, s28, 0x43
	s_cmp_lt_u32 s28, 0x79
	s_cselect_b32 s101, 1, 0
	v_add_f32_e32 v139, 1.0, v202
	v_sub_f32_e32 v141, v141, v202
	v_sqrt_f32_e32 v76, s27
	v_mov_b32_e32 v77, 0
	v_mul_f32_e32 v76, s27, v76
	s_mov_b32 s22, 0
	s_mov_b32 s23, 0
	s_mov_b32 s21, 2
	s_branch .Lsqb_next
.Lsqb_st2:
	s_cmpk_eq_i32 s24, 0x100
	s_cbranch_scc1 .Lsqb_exact
	s_cmpk_gt_i32 s24, 0x100
	s_cbranch_scc0 .Lsqb_s2lt
	s_mov_b32 s13, s14
	s_mov_b32 s98, s24
	v_mov_b32_e32 v76, v146
	s_cmp_eq_u32 s99, 0
	s_cbranch_scc1 .Lsqb_s2ap
	s_add_i32 s27, s75, 2
	s_sub_i32 s27, s27, s24
	v_cvt_f32_u32_e32 v139, s27
	v_add_f32_e32 v139, 0.5, v139
	v_log_f32_e32 v139, v139
	s_cmp_lg_u32 s23, 1
	s_cbranch_scc1 .Lsqb_s2an
	v_mul_f32_e32 v141, 0x3f400000, v141
.Lsqb_s2an:
	v_sub_f32_e32 v139, v202, v139
	s_branch .Lsqb_s2aj
.Lsqb_s2ap:
	v_cvt_f32_u32_e32 v139, s24
	v_log_f32_e32 v139, v139
	s_cmp_lg_u32 s23, 1
	s_cbranch_scc1 .Lsqb_s2a
	v_mul_f32_e32 v141, 0x3f400000, v141

; __device__ __forceinline__ void select_query(const unsigned (&u)[64], unsigned vmax, int q, int b, int lane, unsigned* MASKb) {
;     ...
;             if (c > 256) { lo = mid; Llo = __log2f((float)c) - L256; if (last == 1) Lhi *= 0.5f; last = 1; }
;             else { hi = mid; Lhi = L256 - __log2f(fmaxf((float)c, 0.5f)); if (last == 2) Llo *= 0.5f; last = 2; }
.Lsqb_s2lt:
	s_mov_b32 s12, s14
	s_mov_b32 s15, s24
	v_mov_b32_e32 v77, v146
	s_cmp_eq_u32 s99, 0
	s_cbranch_scc1 .Lsqb_s2bp
	s_add_i32 s27, s75, 2
	s_sub_i32 s27, s27, s24
	v_cvt_f32_u32_e32 v141, s27
	v_add_f32_e32 v141, 0.5, v141
	v_log_f32_e32 v141, v141
	s_cmp_lg_u32 s23, 2
	s_cbranch_scc1 .Lsqb_s2bn
	v_mul_f32_e32 v139, 0x3f400000, v139
.Lsqb_s2bn:
	v_sub_f32_e32 v141, v141, v202
	s_branch .Lsqb_s2bj
.Lsqb_s2bp:
	v_cvt_f32_u32_e32 v141, s24
	v_max_f32_e32 v141, 0.5, v141
	v_log_f32_e32 v141, v141
	s_cmp_lg_u32 s23, 2
	s_cbranch_scc1 .Lsqb_s2b
	v_mul_f32_e32 v139, 0x3f400000, v139

; __device__ __forceinline__ float keyval(unsigned k) { return __uint_as_float((k & 0x80000000u) ? (k ^ 0x80000000u) : ~k); }
; __device__ __forceinline__ unsigned valkey(float f) { const unsigned b = __float_as_uint(f); return b ^ ((unsigned)((int)b >> 31) | 0x80000000u); }
; __device__ __forceinline__ void select_query(const unsigned (&u)[64], unsigned vmax, int q, int b, int lane, unsigned* MASKb) {
;     ...
;             if (hi - lo <= 1u) { T = lo; exact = false; break; }
;             const float vlo = keyval(lo), vhi = keyval(hi);
;             const float frac = (it >= 9 && (it & 1)) ? 0.5f : Llo * __builtin_amdgcn_rcpf(Llo + Lhi);
;             unsigned mid = valkey(vlo + frac * (vhi - vlo));
;             if (mid <= lo) mid = lo + 1u;
;             if (mid >= hi) mid = hi - 1u;
;             mid = __builtin_amdgcn_readfirstlane(mid);
.Lsqb_next:
	s_sub_u32 s26, s12, s13
	s_cmp_lt_u32 s26, 2
	s_cbranch_scc1 .Lsqb_collapse
	s_sub_u32 s26, s98, s15
	s_cmp_le_u32 s26, 4
	s_cbranch_scc1 .Lsqb_endg
	s_cmp_eq_u32 s101, 0
	s_cbranch_scc1 .Lsqb_lin
	s_cmp_lt_i32 s22, 9
	s_cbranch_scc0 .Lsqb_lin
	v_add_f32_e32 v142, v139, v141
	v_sub_f32_e32 v140, v77, v76
	v_rcp_f32_e32 v142, v142
	s_nop 0
	v_mul_f32_e32 v142, v139, v142
	v_fma_f32 v146, v142, v140, v76
	v_log_f32_e32 v138, v146
	s_nop 0
	v_mul_f32_e32 v138, 0x3f2aaaab, v138
	v_exp_f32_e32 v142, v138
	s_nop 0
	s_cmp_eq_u32 s99, 0
	s_cbranch_scc1 .Lsqb_key
	v_xor_b32_e32 v142, 0x80000000, v142
	s_branch .Lsqb_key

; __device__ __forceinline__ float keyval(unsigned k) { return __uint_as_float((k & 0x80000000u) ? (k ^ 0x80000000u) : ~k); }
; __device__ __forceinline__ unsigned valkey(float f) { const unsigned b = __float_as_uint(f); return b ^ ((unsigned)((int)b >> 31) | 0x80000000u); }
; __device__ __forceinline__ void select_query(const unsigned (&u)[64], unsigned vmax, int q, int b, int lane, unsigned* MASKb) {
;     ...
;             if (hi - lo <= 1u) { T = lo; exact = false; break; }
;             const float vlo = keyval(lo), vhi = keyval(hi);
;             const float frac = (it >= 9 && (it & 1)) ? 0.5f : Llo * __builtin_amdgcn_rcpf(Llo + Lhi);
;             unsigned mid = valkey(vlo + frac * (vhi - vlo));
.Lsqb_endg:
	s_cmp_gt_i32 s13, -1
	s_cselect_b32 s26, -1, 0x80000000
	s_xor_b32 s16, s13, s26
	s_cmp_gt_i32 s12, -1
	s_cselect_b32 s26, -1, 0x80000000
	s_xor_b32 s17, s12, s26
	v_mov_b32_e32 v142, 0.5
	s_branch .Lsqb_frac
